# gating phase: end-of-unit workgroup barrier kept only on loop exit (redundant between units: B1/B2 of the next unit order the LDS reuse)
# speedup vs baseline: 1.0064x; 1.0001x over previous
.LBB0_2539:
	v_add_u32_e32 v36, s12, v44
	v_ashrrev_i32_e32 v37, 31, v36
	s_lshl_b32 s34, s12, 1
	s_lshl_b32 s12, s12, 2
	v_lshl_add_u64 v[36:37], v[36:37], 2, s[4:5]
	v_lshl_add_u64 v[92:93], v[48:49], 0, s[12:13]
	global_load_dword v2, v[36:37], off
	global_load_dwordx4 v[72:75], v[92:93], off offset:128
	global_load_dwordx4 v[76:79], v[92:93], off offset:192
	global_load_dwordx4 v[68:71], v[92:93], off offset:64
	global_load_dwordx4 v[80:83], v[92:93], off offset:256
	v_add_u32_e32 v52, s38, v44
	global_load_dwordx4 v[36:39], v[92:93], off
	v_ashrrev_i32_e32 v53, 31, v52
	v_lshlrev_b64 v[52:53], 11, v[52:53]
	v_lshl_add_u64 v[52:53], v[50:51], 0, v[52:53]
	s_mov_b32 s35, s13
	v_lshl_add_u64 v[52:53], v[52:53], 0, s[34:35]
	global_load_dwordx4 v[84:87], v[92:93], off offset:320
	global_load_dwordx2 v[96:97], v[52:53], off
	global_load_dwordx2 v[98:99], v[52:53], off offset:32
	global_load_dwordx2 v[100:101], v[52:53], off offset:64
	global_load_dwordx2 v[102:103], v[52:53], off offset:96
	global_load_dwordx2 v[104:105], v[52:53], off offset:128
	global_load_dwordx2 v[106:107], v[52:53], off offset:160
	global_load_dwordx2 v[108:109], v[52:53], off offset:192
	global_load_dwordx4 v[88:91], v[92:93], off offset:384
	global_load_dwordx2 v[110:111], v[52:53], off offset:224
	s_nop 0
	global_load_dwordx4 v[92:95], v[92:93], off offset:448
	s_add_i32 s33, s33, s0
	s_add_i32 s31, s31, s1
	s_add_i32 s30, s30, s11
	s_cmpk_gt_i32 s33, 0x3ff
	s_waitcnt vmcnt(15)
	v_pk_fma_f32 v[20:21], v[20:21], v[72:73], v[2:3] op_sel_hi:[1,1,0]
	s_waitcnt vmcnt(14)
	v_pk_fma_f32 v[12:13], v[12:13], v[76:77], v[2:3] op_sel_hi:[1,1,0]
	v_pk_fma_f32 v[14:15], v[14:15], v[78:79], v[2:3] op_sel_hi:[1,1,0]
	s_waitcnt vmcnt(13)
	v_pk_fma_f32 v[24:25], v[24:25], v[68:69], v[2:3] op_sel_hi:[1,1,0]
	v_pk_fma_f32 v[26:27], v[26:27], v[70:71], v[2:3] op_sel_hi:[1,1,0]
	s_waitcnt vmcnt(11)
	v_pk_fma_f32 v[28:29], v[28:29], v[36:37], v[2:3] op_sel_hi:[1,1,0]
	v_pk_fma_f32 v[30:31], v[30:31], v[38:39], v[2:3] op_sel_hi:[1,1,0]
	s_waitcnt vmcnt(9)
	v_lshlrev_b32_e32 v36, 16, v96
	v_and_b32_e32 v37, 0xffff0000, v96
	v_lshlrev_b32_e32 v38, 16, v97
	v_and_b32_e32 v39, 0xffff0000, v97
	s_waitcnt vmcnt(6)
	v_lshlrev_b32_e32 v76, 16, v102
	v_and_b32_e32 v77, 0xffff0000, v102
	v_lshlrev_b32_e32 v78, 16, v103
	v_and_b32_e32 v79, 0xffff0000, v103
	v_pk_fma_f32 v[22:23], v[22:23], v[74:75], v[2:3] op_sel_hi:[1,1,0]
	v_pk_fma_f32 v[16:17], v[16:17], v[80:81], v[2:3] op_sel_hi:[1,1,0]
	v_pk_fma_f32 v[18:19], v[18:19], v[82:83], v[2:3] op_sel_hi:[1,1,0]
	v_lshlrev_b32_e32 v68, 16, v98
	v_and_b32_e32 v69, 0xffff0000, v98
	v_lshlrev_b32_e32 v70, 16, v99
	v_and_b32_e32 v71, 0xffff0000, v99
	v_lshlrev_b32_e32 v72, 16, v100
	v_and_b32_e32 v73, 0xffff0000, v100
	v_lshlrev_b32_e32 v74, 16, v101
	v_and_b32_e32 v75, 0xffff0000, v101
	s_waitcnt vmcnt(5)
	v_lshlrev_b32_e32 v80, 16, v104
	v_and_b32_e32 v81, 0xffff0000, v104
	v_lshlrev_b32_e32 v82, 16, v105
	v_and_b32_e32 v83, 0xffff0000, v105
	v_pk_mul_f32 v[28:29], v[28:29], v[36:37]
	v_pk_mul_f32 v[30:31], v[30:31], v[38:39]
	v_pk_mul_f32 v[12:13], v[12:13], v[76:77]
	v_pk_mul_f32 v[14:15], v[14:15], v[78:79]
	v_pk_mul_f32 v[24:25], v[24:25], v[68:69]
	v_pk_mul_f32 v[26:27], v[26:27], v[70:71]
	v_pk_mul_f32 v[20:21], v[20:21], v[72:73]
	v_pk_mul_f32 v[22:23], v[22:23], v[74:75]
	v_pk_mul_f32 v[16:17], v[16:17], v[80:81]
	v_pk_mul_f32 v[18:19], v[18:19], v[82:83]
	v_cvt_pk_bf16_f32 v28, v28, v29
	v_cvt_pk_bf16_f32 v29, v30, v31
	v_cvt_pk_bf16_f32 v12, v12, v13
	v_cvt_pk_bf16_f32 v13, v14, v15
	v_pk_fma_f32 v[8:9], v[8:9], v[84:85], v[2:3] op_sel_hi:[1,1,0]
	s_waitcnt vmcnt(4)
	v_lshlrev_b32_e32 v84, 16, v106
	v_and_b32_e32 v85, 0xffff0000, v106
	v_cvt_pk_bf16_f32 v24, v24, v25
	v_cvt_pk_bf16_f32 v25, v26, v27
	v_cvt_pk_bf16_f32 v20, v20, v21
	v_cvt_pk_bf16_f32 v21, v22, v23
	v_cvt_pk_bf16_f32 v14, v16, v17
	v_cvt_pk_bf16_f32 v15, v18, v19
	global_store_dwordx2 v[52:53], v[28:29], off
	global_store_dwordx2 v[52:53], v[24:25], off offset:32
	global_store_dwordx2 v[52:53], v[20:21], off offset:64
	global_store_dwordx2 v[52:53], v[12:13], off offset:96
	global_store_dwordx2 v[52:53], v[14:15], off offset:128
	v_lshlrev_b32_e32 v12, 16, v107
	v_and_b32_e32 v13, 0xffff0000, v107
	v_pk_fma_f32 v[10:11], v[10:11], v[86:87], v[2:3] op_sel_hi:[1,1,0]
	v_pk_mul_f32 v[8:9], v[8:9], v[84:85]
	v_pk_mul_f32 v[10:11], v[10:11], v[12:13]
	v_cvt_pk_bf16_f32 v8, v8, v9
	v_cvt_pk_bf16_f32 v9, v10, v11
	global_store_dwordx2 v[52:53], v[8:9], off offset:160
	s_waitcnt vmcnt(9)
	v_lshlrev_b32_e32 v8, 16, v108
	v_and_b32_e32 v9, 0xffff0000, v108
	s_waitcnt vmcnt(8)
	v_pk_fma_f32 v[4:5], v[4:5], v[88:89], v[2:3] op_sel_hi:[1,1,0]
	v_pk_fma_f32 v[6:7], v[6:7], v[90:91], v[2:3] op_sel_hi:[1,1,0]
	v_pk_mul_f32 v[4:5], v[4:5], v[8:9]
	v_lshlrev_b32_e32 v8, 16, v109
	v_and_b32_e32 v9, 0xffff0000, v109
	v_pk_mul_f32 v[6:7], v[6:7], v[8:9]
	v_cvt_pk_bf16_f32 v4, v4, v5
	v_cvt_pk_bf16_f32 v5, v6, v7
	global_store_dwordx2 v[52:53], v[4:5], off offset:192
	s_waitcnt vmcnt(8)
	v_lshlrev_b32_e32 v4, 16, v110
	v_and_b32_e32 v5, 0xffff0000, v110
	s_waitcnt vmcnt(7)
	v_pk_fma_f32 v[6:7], v[32:33], v[92:93], v[2:3] op_sel_hi:[1,1,0]
	v_pk_fma_f32 v[8:9], v[34:35], v[94:95], v[2:3] op_sel_hi:[1,1,0]
	v_pk_mul_f32 v[4:5], v[6:7], v[4:5]
	v_lshlrev_b32_e32 v6, 16, v111
	v_and_b32_e32 v7, 0xffff0000, v111
	v_pk_mul_f32 v[6:7], v[8:9], v[6:7]
	v_cvt_pk_bf16_f32 v4, v4, v5
	v_cvt_pk_bf16_f32 v5, v6, v7
	global_store_dwordx2 v[52:53], v[4:5], off offset:224
	s_cbranch_scc1 .Lgate_exit_bar

.Lgate_exit_bar:
	s_barrier
